# P0b and merge output stages: integer RNE f32->bf16 pack (bfe/add3/lshr/and_or, 12 VALU per 4 values) replaced by v_cvt_pk_bf16_f32 (the same RNE conversion the baseline uses elsewhere)
# speedup vs baseline: 1.0150x; 1.0003x over previous
.LBB0_138:
	v_lshl_add_u64 v[2:3], s[36:37], 0, v[204:205]
	v_lshl_add_u64 v[4:5], s[70:71], 0, v[204:205]
	v_lshl_add_u64 v[10:11], s[62:63], 0, v[204:205]
	v_lshl_add_u64 v[70:71], s[56:57], 0, v[204:205]
	global_load_dwordx4 v[6:9], v[74:75], off
	global_load_dwordx4 v[66:69], v[2:3], off
	global_load_dwordx4 v[58:61], v[2:3], off offset:1024
	global_load_dwordx4 v[54:57], v[2:3], off offset:3072
	global_load_dwordx4 v[62:65], v[2:3], off offset:2048
	global_load_dwordx4 v[50:53], v[4:5], off
	global_load_dwordx4 v[42:45], v[4:5], off offset:1024
	global_load_dwordx4 v[38:41], v[4:5], off offset:3072
	global_load_dwordx4 v[46:49], v[4:5], off offset:2048
	global_load_dwordx4 v[34:37], v[10:11], off
	global_load_dwordx4 v[30:33], v[10:11], off offset:1024
	global_load_dwordx4 v[26:29], v[10:11], off offset:2048
	global_load_dwordx4 v[22:25], v[10:11], off offset:3072
	global_load_dwordx4 v[18:21], v[70:71], off
	global_load_dwordx4 v[14:17], v[70:71], off offset:1024
	s_nop 0
	global_load_dwordx4 v[10:13], v[70:71], off offset:2048
	global_load_dwordx4 v[2:5], v[70:71], off offset:3072
	s_ashr_i32 s0, s38, 13
	v_lshl_add_u64 v[72:73], s[60:61], 0, v[200:201]
	v_lshl_add_u64 v[76:77], s[68:69], 0, v[200:201]
	s_mul_i32 s8, s0, 0x1800
	v_add_co_u32_e32 v82, vcc, s33, v72
	v_add_co_u32_e64 v80, s[0:1], s33, v76
	s_ashr_i32 s9, s8, 31
	v_addc_co_u32_e32 v83, vcc, 0, v73, vcc
	v_addc_co_u32_e64 v81, vcc, 0, v77, s[0:1]
	s_lshl_b64 s[0:1], s[8:9], 2
	s_add_u32 s78, s28, s0
	s_addc_u32 s79, s29, s1
	v_lshl_add_u64 v[96:97], s[30:31], 0, v[200:201]
	s_add_u32 s80, s78, 0x1000
	v_add_co_u32_e64 v76, s[6:7], s33, v96
	s_addc_u32 s81, s79, 0
	s_nop 0
	v_addc_co_u32_e64 v77, vcc, 0, v97, s[6:7]
	global_load_dwordx4 v[70:73], v92, s[78:79]
	global_load_dwordx4 v[96:99], v92, s[80:81]
	s_add_i32 s0, s38, 0x800
	s_ashr_i32 s0, s0, 13
	s_mulk_i32 s0, 0x1800
	s_ashr_i32 s1, s0, 31
	s_lshl_b64 s[0:1], s[0:1], 2
	s_add_u32 s54, s28, s0
	s_addc_u32 s55, s29, s1
	s_add_u32 s74, s54, 0x1000
	s_addc_u32 s75, s55, 0
	s_add_i32 s0, s38, 0x1000
	s_ashr_i32 s0, s0, 13
	s_mulk_i32 s0, 0x1800
	s_ashr_i32 s1, s0, 31
	s_lshl_b64 s[0:1], s[0:1], 2
	s_add_u32 s66, s28, s0
	s_addc_u32 s67, s29, s1
	s_add_u32 s72, s66, 0x1000
	s_addc_u32 s73, s67, 0
	s_add_i32 s0, s38, 0x1800
	v_lshl_add_u64 v[78:79], s[58:59], 0, v[200:201]
	s_ashr_i32 s0, s0, 13
	v_add_co_u32_e64 v78, s[4:5], s33, v78
	s_mulk_i32 s0, 0x1800
	s_nop 0
	v_addc_co_u32_e64 v79, vcc, 0, v79, s[4:5]
	s_ashr_i32 s1, s0, 31
	s_lshl_b64 s[0:1], s[0:1], 2
	s_add_u32 s52, s28, s0
	s_addc_u32 s53, s29, s1
	s_add_u32 s64, s52, 0x1000
	s_addc_u32 s65, s53, 0
	s_add_u32 s30, s30, 0x1000000
	s_addc_u32 s31, s31, 0
	s_add_u32 s36, s36, 0x2000000
	s_addc_u32 s37, s37, 0
	s_add_u32 s56, s56, 0x2000000
	s_addc_u32 s57, s57, 0
	s_add_u32 s58, s58, 0x1000000
	s_waitcnt vmcnt(17)
	v_pk_mul_f32 v[100:101], v[68:69], v[68:69]
	v_pk_mul_f32 v[102:103], v[66:67], v[66:67]
	s_waitcnt vmcnt(16)
	v_pk_mul_f32 v[104:105], v[60:61], v[60:61]
	v_pk_mul_f32 v[106:107], v[58:59], v[58:59]
	s_waitcnt vmcnt(13)
	v_pk_mul_f32 v[112:113], v[52:53], v[52:53]
	v_pk_mul_f32 v[114:115], v[50:51], v[50:51]
	s_waitcnt vmcnt(12)
	v_pk_mul_f32 v[116:117], v[44:45], v[44:45]
	v_pk_mul_f32 v[118:119], v[42:43], v[42:43]
	v_mul_f32_e32 v109, v56, v56
	v_mul_f32_e32 v108, v63, v63
	v_mul_f32_e32 v110, v65, v65
	s_waitcnt vmcnt(10)
	v_mul_f32_e32 v120, v47, v47
	v_mul_f32_e32 v122, v49, v49
	s_waitcnt vmcnt(9)
	v_pk_mul_f32 v[124:125], v[36:37], v[36:37]
	v_pk_mul_f32 v[126:127], v[34:35], v[34:35]
	s_waitcnt vmcnt(8)
	v_pk_mul_f32 v[128:129], v[32:33], v[32:33]
	v_pk_mul_f32 v[130:131], v[30:31], v[30:31]
	v_pk_mov_b32 v[140:141], v[102:103], v[100:101] op_sel:[1,0]
	v_mov_b32_e32 v103, v101
	v_pk_mov_b32 v[100:101], v[106:107], v[104:105] op_sel:[1,0]
	v_mov_b32_e32 v107, v105
	v_pk_mov_b32 v[104:105], v[114:115], v[112:113] op_sel:[1,0]
	v_mov_b32_e32 v115, v113
	v_pk_mov_b32 v[112:113], v[118:119], v[116:117] op_sel:[1,0]
	v_mov_b32_e32 v119, v117
	v_mul_f32_e32 v144, v57, v57
	v_mul_f32_e32 v147, v40, v40
	v_mul_f32_e32 v149, v41, v41
	s_waitcnt vmcnt(5)
	v_pk_mul_f32 v[132:133], v[20:21], v[20:21]
	v_pk_mul_f32 v[134:135], v[18:19], v[18:19]
	s_waitcnt vmcnt(4)
	v_pk_mul_f32 v[136:137], v[16:17], v[16:17]
	v_pk_mul_f32 v[138:139], v[14:15], v[14:15]
	v_pk_mov_b32 v[116:117], v[126:127], v[124:125] op_sel:[1,0]
	v_mov_b32_e32 v127, v125
	v_pk_mov_b32 v[124:125], v[130:131], v[128:129] op_sel:[1,0]
	v_mov_b32_e32 v131, v129
	v_pk_add_f32 v[102:103], v[140:141], v[102:103]
	v_pk_add_f32 v[100:101], v[100:101], v[106:107]
	v_pk_fma_f32 v[106:107], v[62:63], v[62:63], v[108:109] op_sel_hi:[1,1,0]
	v_pk_add_f32 v[112:113], v[112:113], v[118:119]
	v_pk_fma_f32 v[110:111], v[64:65], v[64:65], v[110:111] op_sel_hi:[1,1,0]
	v_pk_fma_f32 v[118:119], v[46:47], v[46:47], v[120:121] op_sel_hi:[1,1,0]
	v_pk_fma_f32 v[120:121], v[48:49], v[48:49], v[122:123] op_sel_hi:[1,1,0]
	v_mul_f32_e32 v142, v54, v54
	v_mul_f32_e32 v143, v55, v55
	v_pk_mov_b32 v[128:129], v[134:135], v[132:133] op_sel:[1,0]
	v_mov_b32_e32 v135, v133
	v_pk_mov_b32 v[132:133], v[138:139], v[136:137] op_sel:[1,0]
	v_mul_f32_e32 v136, v27, v27
	v_mul_f32_e32 v140, v29, v29
	s_waitcnt vmcnt(2)
	global_load_dwordx4 v[158:161], v[74:75], off
	global_load_dwordx4 v[174:177], v92, s[80:81]
	global_load_dwordx4 v[190:193], v92, s[78:79]
	global_load_dwordx4 v[162:165], v[74:75], off offset:1024
	global_load_dwordx4 v[178:181], v93, s[80:81]
	global_load_dwordx4 v[194:197], v92, s[78:79] offset:1024
	global_load_dwordx4 v[166:169], v[74:75], off offset:2048
	global_load_dwordx4 v[182:185], v94, s[80:81]
	global_load_dwordx4 v[206:209], v92, s[78:79] offset:2048
	global_load_dwordx4 v[170:173], v[74:75], off offset:3072
	global_load_dwordx4 v[186:189], v95, s[80:81]
	global_load_dwordx4 v[210:213], v92, s[78:79] offset:3072
	v_mul_f32_e32 v141, v2, v2
	v_mov_b32_e32 v107, v109
	v_pk_add_f32 v[104:105], v[104:105], v[114:115]
	v_mov_b32_e32 v111, v144
	v_mov_b32_e32 v119, v147
	v_mov_b32_e32 v121, v149
	v_pk_add_f32 v[116:117], v[116:117], v[126:127]
	v_pk_add_f32 v[124:125], v[124:125], v[130:131]
	v_pk_add_f32 v[102:103], v[102:103], v[102:103] op_sel:[0,1] op_sel_hi:[1,0]
	v_pk_add_f32 v[100:101], v[100:101], v[100:101] op_sel:[0,1] op_sel_hi:[1,0]
	v_mul_f32_e32 v145, v38, v38
	v_mul_f32_e32 v146, v39, v39
	v_mul_f32_e32 v150, v22, v22
	v_mul_f32_e32 v151, v23, v23
	v_mul_f32_e32 v152, v24, v24
	v_mul_f32_e32 v153, v25, v25
	v_mov_b32_e32 v139, v137
	v_pk_fma_f32 v[122:123], v[26:27], v[26:27], v[136:137] op_sel_hi:[1,1,0]
	v_pk_fma_f32 v[136:137], v[28:29], v[28:29], v[140:141] op_sel_hi:[1,1,0]
	v_pk_add_f32 v[106:107], v[106:107], v[110:111]
	v_pk_add_f32 v[104:105], v[104:105], v[104:105] op_sel:[0,1] op_sel_hi:[1,0]
	v_pk_add_f32 v[110:111], v[112:113], v[112:113] op_sel:[0,1] op_sel_hi:[1,0]
	v_pk_add_f32 v[112:113], v[118:119], v[120:121]
	v_pk_add_f32 v[116:117], v[116:117], v[116:117] op_sel:[0,1] op_sel_hi:[1,0]
	v_pk_add_f32 v[118:119], v[124:125], v[124:125] op_sel:[0,1] op_sel_hi:[1,0]
	v_mov_b32_e32 v103, v142
	v_mov_b32_e32 v101, v143
	v_mov_b32_e32 v123, v152
	v_mov_b32_e32 v137, v153
	v_mov_b32_e32 v105, v145
	v_mov_b32_e32 v111, v146
	v_mov_b32_e32 v117, v150
	v_mov_b32_e32 v119, v151
	v_pk_add_f32 v[100:101], v[102:103], v[100:101]
	v_mul_f32_e32 v108, v11, v11
	v_mul_f32_e32 v114, v13, v13
	v_pk_add_f32 v[126:127], v[128:129], v[134:135]
	v_pk_add_f32 v[128:129], v[132:133], v[138:139]
	v_pk_add_f32 v[120:121], v[122:123], v[136:137]
	v_pk_add_f32 v[102:103], v[104:105], v[110:111]
	v_pk_add_f32 v[104:105], v[116:117], v[118:119]
	v_pk_add_f32 v[100:101], v[100:101], v[106:107]
	v_mul_f32_e32 v154, v3, v3
	v_mul_f32_e32 v155, v4, v4
	v_mul_f32_e32 v156, v5, v5
	v_pk_fma_f32 v[108:109], v[10:11], v[10:11], v[108:109] op_sel_hi:[1,1,0]
	v_pk_fma_f32 v[114:115], v[12:13], v[12:13], v[114:115] op_sel_hi:[1,1,0]
	v_pk_add_f32 v[122:123], v[126:127], v[126:127] op_sel:[0,1] op_sel_hi:[1,0]
	v_pk_add_f32 v[124:125], v[128:129], v[128:129] op_sel:[0,1] op_sel_hi:[1,0]
	v_pk_add_f32 v[102:103], v[102:103], v[112:113]
	v_pk_add_f32 v[104:105], v[104:105], v[120:121]
	v_add_f32_e32 v100, v100, v101
	v_mov_b32_e32 v109, v155
	v_mov_b32_e32 v115, v156
	v_mov_b32_e32 v123, v141
	v_mov_b32_e32 v125, v154
	v_add_f32_e32 v101, v102, v103
	v_add_f32_e32 v102, v104, v105
	ds_bpermute_b32 v104, v84, v100
	v_pk_add_f32 v[108:109], v[108:109], v[114:115]
	v_pk_add_f32 v[110:111], v[122:123], v[124:125]
	ds_bpermute_b32 v105, v84, v101
	v_pk_add_f32 v[106:107], v[110:111], v[108:109]
	s_waitcnt lgkmcnt(1)
	v_add_f32_e32 v100, v100, v104
	v_add_f32_e32 v103, v106, v107
	ds_bpermute_b32 v106, v84, v102
	ds_bpermute_b32 v104, v85, v100
	s_waitcnt lgkmcnt(2)
	v_add_f32_e32 v101, v101, v105
	ds_bpermute_b32 v105, v85, v101
	ds_bpermute_b32 v107, v84, v103
	s_waitcnt lgkmcnt(3)
	v_add_f32_e32 v102, v102, v106
	ds_bpermute_b32 v106, v85, v102
	s_waitcnt lgkmcnt(3)
	v_add_f32_e32 v100, v100, v104
	ds_bpermute_b32 v104, v86, v100
	s_waitcnt lgkmcnt(3)
	v_add_f32_e32 v101, v101, v105
	ds_bpermute_b32 v105, v86, v101
	s_waitcnt lgkmcnt(2)
	v_add_f32_e32 v102, v102, v106
	ds_bpermute_b32 v106, v86, v102
	s_waitcnt lgkmcnt(2)
	v_add_f32_e32 v100, v100, v104
	ds_bpermute_b32 v104, v87, v100
	s_waitcnt lgkmcnt(2)
	v_add_f32_e32 v101, v101, v105
	ds_bpermute_b32 v105, v87, v101
	s_waitcnt lgkmcnt(2)
	v_add_f32_e32 v102, v102, v106
	ds_bpermute_b32 v106, v87, v102
	s_waitcnt lgkmcnt(2)
	v_add_f32_e32 v100, v100, v104
	ds_bpermute_b32 v104, v88, v100
	s_waitcnt lgkmcnt(2)
	v_add_f32_e32 v101, v101, v105
	ds_bpermute_b32 v105, v88, v101
	s_waitcnt lgkmcnt(2)
	v_add_f32_e32 v102, v102, v106
	ds_bpermute_b32 v106, v88, v102
	s_waitcnt lgkmcnt(2)
	v_add_f32_e32 v100, v100, v104
	ds_bpermute_b32 v104, v89, v100
	v_add_f32_e32 v103, v103, v107
	s_waitcnt lgkmcnt(2)
	v_add_f32_e32 v101, v101, v105
	ds_bpermute_b32 v107, v85, v103
	s_waitcnt lgkmcnt(2)
	v_add_f32_e32 v102, v102, v106
	ds_bpermute_b32 v105, v89, v101
	ds_bpermute_b32 v106, v89, v102
	s_waitcnt lgkmcnt(3)
	v_add_f32_e32 v100, v100, v104
	v_fmamk_f32 v100, v100, 0x3a800000, v90
	s_waitcnt lgkmcnt(2)
	v_add_f32_e32 v103, v103, v107
	s_waitcnt lgkmcnt(1)
	v_add_f32_e32 v101, v101, v105
	v_cmp_gt_f32_e32 vcc, s3, v100
	v_mul_f32_e32 v104, 0x4f800000, v100
	ds_bpermute_b32 v107, v86, v103
	s_waitcnt lgkmcnt(1)
	v_add_f32_e32 v102, v102, v106
	v_fmamk_f32 v101, v101, 0x3a800000, v90
	v_cndmask_b32_e32 v100, v100, v104, vcc
	v_fmamk_f32 v102, v102, 0x3a800000, v90
	v_cmp_gt_f32_e64 s[0:1], s3, v101
	v_mul_f32_e32 v105, 0x4f800000, v101
	v_sqrt_f32_e32 v104, v100
	v_cmp_gt_f32_e64 s[4:5], s3, v102
	v_mul_f32_e32 v106, 0x4f800000, v102
	v_cndmask_b32_e64 v101, v101, v105, s[0:1]
	v_cndmask_b32_e64 v102, v102, v106, s[4:5]
	v_sqrt_f32_e32 v105, v101
	v_sqrt_f32_e32 v106, v102
	s_waitcnt lgkmcnt(0)
	v_add_f32_e32 v103, v103, v107
	v_add_u32_e32 v107, -1, v104
	v_add_u32_e32 v108, 1, v104
	v_fma_f32 v113, -v107, v104, v100
	v_add_u32_e32 v109, -1, v105
	v_fma_f32 v114, -v108, v104, v100
	v_cmp_ge_f32_e64 s[12:13], 0, v113
	v_add_u32_e32 v110, 1, v105
	v_add_u32_e32 v111, -1, v106
	v_fma_f32 v115, -v109, v105, v101
	v_cmp_lt_f32_e64 s[16:17], 0, v114
	v_cndmask_b32_e64 v104, v104, v107, s[12:13]
	v_add_u32_e32 v112, 1, v106
	v_fma_f32 v116, -v110, v105, v101
	v_fma_f32 v117, -v111, v106, v102
	v_cmp_ge_f32_e64 s[18:19], 0, v115
	v_cndmask_b32_e64 v104, v104, v108, s[16:17]
	v_fma_f32 v118, -v112, v106, v102
	v_cmp_lt_f32_e64 s[20:21], 0, v116
	v_cmp_ge_f32_e64 s[22:23], 0, v117
	v_cndmask_b32_e64 v105, v105, v109, s[18:19]
	v_mul_f32_e32 v107, 0x37800000, v104
	v_cmp_class_f32_e64 s[6:7], v100, v91
	v_cmp_lt_f32_e64 s[24:25], 0, v118
	v_cndmask_b32_e64 v106, v106, v111, s[22:23]
	v_cndmask_b32_e64 v105, v105, v110, s[20:21]
	v_cndmask_b32_e32 v104, v104, v107, vcc
	v_cndmask_b32_e64 v106, v106, v112, s[24:25]
	v_mul_f32_e32 v108, 0x37800000, v105
	v_cndmask_b32_e64 v100, v104, v100, s[6:7]
	v_cmp_class_f32_e64 s[8:9], v101, v91
	v_mul_f32_e32 v109, 0x37800000, v106
	v_cndmask_b32_e64 v105, v105, v108, s[0:1]
	v_div_scale_f32 v104, s[0:1], v100, v100, 1.0
	v_cmp_class_f32_e64 s[10:11], v102, v91
	v_cndmask_b32_e64 v106, v106, v109, s[4:5]
	v_cndmask_b32_e64 v101, v105, v101, s[8:9]
	v_rcp_f32_e32 v110, v104
	v_cndmask_b32_e64 v102, v106, v102, s[10:11]
	v_div_scale_f32 v106, s[0:1], v101, v101, 1.0
	v_div_scale_f32 v108, s[4:5], v102, v102, 1.0
	v_rcp_f32_e32 v111, v106
	v_rcp_f32_e32 v112, v108
	v_fma_f32 v113, -v104, v110, 1.0
	v_div_scale_f32 v105, vcc, 1.0, v100, 1.0
	v_fmac_f32_e32 v110, v113, v110
	v_fma_f32 v114, -v106, v111, 1.0
	v_mul_f32_e32 v113, v105, v110
	v_div_scale_f32 v107, s[0:1], 1.0, v101, 1.0
	v_fma_f32 v115, -v108, v112, 1.0
	v_fmac_f32_e32 v111, v114, v111
	v_fma_f32 v116, -v104, v113, v105
	v_div_scale_f32 v109, s[4:5], 1.0, v102, 1.0
	v_fmac_f32_e32 v112, v115, v112
	v_mul_f32_e32 v114, v107, v111
	v_fmac_f32_e32 v113, v116, v110
	v_mul_f32_e32 v115, v109, v112
	v_fma_f32 v117, -v106, v114, v107
	v_fma_f32 v104, -v104, v113, v105
	v_fma_f32 v118, -v108, v115, v109
	v_fmac_f32_e32 v114, v117, v111
	v_div_fmas_f32 v104, v104, v110, v113
	v_fmac_f32_e32 v115, v118, v112
	v_fma_f32 v105, -v106, v114, v107
	v_div_fixup_f32 v100, v104, v100, 1.0
	s_mov_b64 vcc, s[0:1]
	v_fma_f32 v106, -v108, v115, v109
	v_div_fmas_f32 v104, v105, v111, v114
	v_pk_mul_f32 v[68:69], v[68:69], v[100:101] op_sel_hi:[1,0]
	v_pk_mul_f32 v[66:67], v[66:67], v[100:101] op_sel_hi:[1,0]
	s_mov_b64 vcc, s[4:5]
	s_waitcnt vmcnt(0)
	v_pk_add_f32 v[98:99], v[98:99], 1.0 op_sel_hi:[1,0]
	v_pk_add_f32 v[96:97], v[96:97], 1.0 op_sel_hi:[1,0]
	v_pk_mul_f32 v[60:61], v[60:61], v[100:101] op_sel_hi:[1,0]
	v_pk_mul_f32 v[58:59], v[58:59], v[100:101] op_sel_hi:[1,0]
	v_pk_mul_f32 v[64:65], v[64:65], v[100:101] op_sel_hi:[1,0]
	v_pk_mul_f32 v[62:63], v[62:63], v[100:101] op_sel_hi:[1,0]
	v_pk_mul_f32 v[56:57], v[56:57], v[100:101] op_sel_hi:[1,0]
	v_pk_mul_f32 v[54:55], v[54:55], v[100:101] op_sel_hi:[1,0]
	v_div_fixup_f32 v100, v104, v101, 1.0
	v_div_fmas_f32 v104, v106, v112, v115
	v_pk_mul_f32 v[66:67], v[6:7], v[66:67]
	v_pk_mul_f32 v[8:9], v[8:9], v[68:69]
	v_pk_mul_f32 v[52:53], v[52:53], v[100:101] op_sel_hi:[1,0]
	v_pk_mul_f32 v[50:51], v[50:51], v[100:101] op_sel_hi:[1,0]
	v_pk_mul_f32 v[44:45], v[44:45], v[100:101] op_sel_hi:[1,0]
	v_pk_mul_f32 v[42:43], v[42:43], v[100:101] op_sel_hi:[1,0]
	v_pk_mul_f32 v[48:49], v[48:49], v[100:101] op_sel_hi:[1,0]
	v_pk_mul_f32 v[46:47], v[46:47], v[100:101] op_sel_hi:[1,0]
	v_pk_mul_f32 v[68:69], v[40:41], v[100:101] op_sel_hi:[1,0]
	v_pk_mul_f32 v[100:101], v[38:39], v[100:101] op_sel_hi:[1,0]
	v_div_fixup_f32 v6, v104, v102, 1.0
	v_pk_fma_f32 v[8:9], v[98:99], v[8:9], v[72:73]
	v_pk_fma_f32 v[38:39], v[96:97], v[66:67], v[70:71]
	v_pk_mul_f32 v[66:67], v[36:37], v[6:7] op_sel_hi:[1,0]
	v_pk_mul_f32 v[70:71], v[34:35], v[6:7] op_sel_hi:[1,0]
	v_pk_mul_f32 v[72:73], v[32:33], v[6:7] op_sel_hi:[1,0]
	v_pk_mul_f32 v[96:97], v[30:31], v[6:7] op_sel_hi:[1,0]
	v_cvt_pk_bf16_f32 v9, v8, v9
	v_cvt_pk_bf16_f32 v8, v38, v39
	global_store_dwordx2 v[82:83], v[8:9], off
	s_addc_u32 s59, s59, 0
	s_add_u32 s60, s60, 0x1000000
	s_addc_u32 s61, s61, 0
	s_add_u32 s62, s62, 0x2000000
	s_addc_u32 s63, s63, 0
	s_add_u32 s68, s68, 0x1000000
	s_addc_u32 s69, s69, 0
	s_add_u32 s70, s70, 0x2000000
	s_addc_u32 s71, s71, 0
	v_pk_mul_f32 v[8:9], v[162:163], v[58:59]
	v_pk_mul_f32 v[30:31], v[164:165], v[60:61]
	v_pk_add_f32 v[32:33], v[180:181], 1.0 op_sel_hi:[1,0]
	v_pk_add_f32 v[34:35], v[178:179], 1.0 op_sel_hi:[1,0]
	v_pk_fma_f32 v[30:31], v[32:33], v[30:31], v[196:197]
	v_pk_fma_f32 v[8:9], v[34:35], v[8:9], v[194:195]
	v_cvt_pk_bf16_f32 v8, v8, v9
	v_cvt_pk_bf16_f32 v9, v30, v31
	global_store_dwordx2 v[82:83], v[8:9], off offset:512
	v_pk_mul_f32 v[8:9], v[166:167], v[62:63]
	v_pk_mul_f32 v[30:31], v[168:169], v[64:65]
	v_pk_add_f32 v[32:33], v[184:185], 1.0 op_sel_hi:[1,0]
	v_pk_add_f32 v[34:35], v[182:183], 1.0 op_sel_hi:[1,0]
	v_pk_fma_f32 v[30:31], v[30:31], v[32:33], v[208:209]
	v_pk_fma_f32 v[8:9], v[8:9], v[34:35], v[206:207]
	v_cvt_pk_bf16_f32 v8, v8, v9
	v_cvt_pk_bf16_f32 v9, v30, v31
	global_store_dwordx2 v[82:83], v[8:9], off offset:1024
	v_pk_mul_f32 v[8:9], v[54:55], v[170:171]
	v_pk_mul_f32 v[30:31], v[56:57], v[172:173]
	v_pk_add_f32 v[32:33], v[188:189], 1.0 op_sel_hi:[1,0]
	v_pk_add_f32 v[34:35], v[186:187], 1.0 op_sel_hi:[1,0]
	v_pk_fma_f32 v[30:31], v[30:31], v[32:33], v[212:213]
	v_pk_fma_f32 v[8:9], v[8:9], v[34:35], v[210:211]
	v_cvt_pk_bf16_f32 v8, v8, v9
	v_cvt_pk_bf16_f32 v9, v30, v31
	global_store_dwordx2 v[82:83], v[8:9], off offset:1536
	v_pk_mul_f32 v[8:9], v[158:159], v[50:51]
	v_pk_mul_f32 v[30:31], v[160:161], v[52:53]
	v_pk_add_f32 v[32:33], v[176:177], 1.0 op_sel_hi:[1,0]
	v_pk_add_f32 v[34:35], v[174:175], 1.0 op_sel_hi:[1,0]
	v_pk_fma_f32 v[30:31], v[32:33], v[30:31], v[192:193]
	v_pk_fma_f32 v[8:9], v[34:35], v[8:9], v[190:191]
	v_cvt_pk_bf16_f32 v8, v8, v9
	v_cvt_pk_bf16_f32 v9, v30, v31
	global_store_dwordx2 v[80:81], v[8:9], off
	v_pk_mul_f32 v[8:9], v[162:163], v[42:43]
	v_pk_mul_f32 v[30:31], v[164:165], v[44:45]
	v_pk_add_f32 v[32:33], v[180:181], 1.0 op_sel_hi:[1,0]
	v_pk_add_f32 v[34:35], v[178:179], 1.0 op_sel_hi:[1,0]
	v_pk_fma_f32 v[30:31], v[32:33], v[30:31], v[196:197]
	v_pk_fma_f32 v[8:9], v[34:35], v[8:9], v[194:195]
	v_cvt_pk_bf16_f32 v8, v8, v9
	v_cvt_pk_bf16_f32 v9, v30, v31
	global_store_dwordx2 v[80:81], v[8:9], off offset:512
	v_pk_mul_f32 v[8:9], v[166:167], v[46:47]
	v_pk_mul_f32 v[30:31], v[168:169], v[48:49]
	v_pk_add_f32 v[32:33], v[184:185], 1.0 op_sel_hi:[1,0]
	v_pk_add_f32 v[34:35], v[182:183], 1.0 op_sel_hi:[1,0]
	v_pk_fma_f32 v[30:31], v[30:31], v[32:33], v[208:209]
	v_pk_fma_f32 v[8:9], v[8:9], v[34:35], v[206:207]
	v_cvt_pk_bf16_f32 v8, v8, v9
	v_cvt_pk_bf16_f32 v9, v30, v31
	global_store_dwordx2 v[80:81], v[8:9], off offset:1024
	v_pk_mul_f32 v[8:9], v[100:101], v[170:171]
	v_pk_mul_f32 v[30:31], v[68:69], v[172:173]
	v_pk_add_f32 v[32:33], v[188:189], 1.0 op_sel_hi:[1,0]
	v_pk_add_f32 v[34:35], v[186:187], 1.0 op_sel_hi:[1,0]
	v_pk_fma_f32 v[30:31], v[30:31], v[32:33], v[212:213]
	v_pk_fma_f32 v[8:9], v[8:9], v[34:35], v[210:211]
	v_cvt_pk_bf16_f32 v8, v8, v9
	v_cvt_pk_bf16_f32 v9, v30, v31
	global_store_dwordx2 v[80:81], v[8:9], off offset:1536
	v_pk_mul_f32 v[8:9], v[158:159], v[70:71]
	v_pk_mul_f32 v[30:31], v[160:161], v[66:67]
	v_pk_add_f32 v[32:33], v[176:177], 1.0 op_sel_hi:[1,0]
	v_pk_add_f32 v[34:35], v[174:175], 1.0 op_sel_hi:[1,0]
	v_pk_fma_f32 v[30:31], v[32:33], v[30:31], v[192:193]
	v_pk_fma_f32 v[8:9], v[34:35], v[8:9], v[190:191]
	v_cvt_pk_bf16_f32 v8, v8, v9
	v_cvt_pk_bf16_f32 v9, v30, v31
	global_store_dwordx2 v[78:79], v[8:9], off
	v_pk_mul_f32 v[8:9], v[162:163], v[96:97]
	v_pk_mul_f32 v[30:31], v[164:165], v[72:73]
	v_pk_add_f32 v[32:33], v[180:181], 1.0 op_sel_hi:[1,0]
	v_pk_add_f32 v[34:35], v[178:179], 1.0 op_sel_hi:[1,0]
	v_pk_fma_f32 v[30:31], v[32:33], v[30:31], v[196:197]
	v_pk_fma_f32 v[8:9], v[34:35], v[8:9], v[194:195]
	v_cvt_pk_bf16_f32 v8, v8, v9
	v_cvt_pk_bf16_f32 v9, v30, v31
	global_store_dwordx2 v[78:79], v[8:9], off offset:512
	ds_bpermute_b32 v7, v87, v103
	s_waitcnt lgkmcnt(0)
	v_add_f32_e32 v7, v103, v7
	v_pk_mul_f32 v[8:9], v[28:29], v[6:7] op_sel_hi:[1,0]
	v_pk_mul_f32 v[26:27], v[26:27], v[6:7] op_sel_hi:[1,0]
	v_pk_mul_f32 v[8:9], v[168:169], v[8:9]
	v_pk_mul_f32 v[26:27], v[166:167], v[26:27]
	v_pk_add_f32 v[28:29], v[184:185], 1.0 op_sel_hi:[1,0]
	v_pk_add_f32 v[30:31], v[182:183], 1.0 op_sel_hi:[1,0]
	v_pk_fma_f32 v[8:9], v[8:9], v[28:29], v[208:209]
	v_pk_fma_f32 v[26:27], v[26:27], v[30:31], v[206:207]
	v_cvt_pk_bf16_f32 v9, v8, v9
	v_cvt_pk_bf16_f32 v8, v26, v27
	global_store_dwordx2 v[78:79], v[8:9], off offset:1024
	ds_bpermute_b32 v8, v88, v7
	s_waitcnt lgkmcnt(0)
	v_add_f32_e32 v7, v7, v8
	ds_bpermute_b32 v8, v89, v7
	s_waitcnt lgkmcnt(0)
	v_add_f32_e32 v7, v7, v8
	v_fmamk_f32 v7, v7, 0x3a800000, v90
	v_cmp_gt_f32_e32 vcc, s3, v7
	v_mul_f32_e32 v8, 0x4f800000, v7
	s_nop 0
	v_cndmask_b32_e32 v38, v7, v8, vcc
	v_pk_mul_f32 v[8:9], v[24:25], v[6:7] op_sel_hi:[1,0]
	v_pk_mul_f32 v[6:7], v[22:23], v[6:7] op_sel_hi:[1,0]
	v_sqrt_f32_e32 v39, v38
	v_cmp_class_f32_e64 s[0:1], v38, v91
	v_pk_mul_f32 v[6:7], v[6:7], v[170:171]
	v_pk_mul_f32 v[8:9], v[8:9], v[172:173]
	v_pk_add_f32 v[22:23], v[188:189], 1.0 op_sel_hi:[1,0]
	v_pk_add_f32 v[24:25], v[186:187], 1.0 op_sel_hi:[1,0]
	v_pk_fma_f32 v[8:9], v[8:9], v[22:23], v[212:213]
	v_pk_fma_f32 v[6:7], v[6:7], v[24:25], v[210:211]
	v_cvt_pk_bf16_f32 v6, v6, v7
	v_cvt_pk_bf16_f32 v7, v8, v9
	global_store_dwordx2 v[78:79], v[6:7], off offset:1536
	v_add_u32_e32 v6, -1, v39
	v_add_u32_e32 v7, 1, v39
	v_fma_f32 v8, -v6, v39, v38
	v_fma_f32 v9, -v7, v39, v38
	v_cmp_ge_f32_e64 s[4:5], 0, v8
	v_cmp_lt_f32_e64 s[6:7], 0, v9
	s_nop 0
	v_cndmask_b32_e64 v6, v39, v6, s[4:5]
	v_cndmask_b32_e64 v6, v6, v7, s[6:7]
	v_mul_f32_e32 v7, 0x37800000, v6
	v_cndmask_b32_e32 v6, v6, v7, vcc
	v_cndmask_b32_e64 v6, v6, v38, s[0:1]
	v_div_scale_f32 v7, s[0:1], v6, v6, 1.0
	v_rcp_f32_e32 v9, v7
	v_div_scale_f32 v8, vcc, 1.0, v6, 1.0
	s_add_i32 s0, s38, 0x2000
	v_fma_f32 v34, -v7, v9, 1.0
	v_fmac_f32_e32 v9, v34, v9
	v_mul_f32_e32 v34, v8, v9
	v_fma_f32 v35, -v7, v34, v8
	v_fmac_f32_e32 v34, v35, v9
	v_fma_f32 v7, -v7, v34, v8
	v_div_fmas_f32 v7, v7, v9, v34
	v_div_fixup_f32 v6, v7, v6, 1.0
	v_pk_mul_f32 v[8:9], v[20:21], v[6:7] op_sel_hi:[1,0]
	v_pk_mul_f32 v[18:19], v[18:19], v[6:7] op_sel_hi:[1,0]
	s_cmpk_lt_i32 s38, 0x2000
	s_mov_b32 s38, s0
	v_pk_mul_f32 v[18:19], v[158:159], v[18:19]
	v_pk_mul_f32 v[8:9], v[160:161], v[8:9]
	v_pk_add_f32 v[20:21], v[176:177], 1.0 op_sel_hi:[1,0]
	v_pk_add_f32 v[22:23], v[174:175], 1.0 op_sel_hi:[1,0]
	v_pk_fma_f32 v[8:9], v[20:21], v[8:9], v[192:193]
	v_pk_fma_f32 v[18:19], v[22:23], v[18:19], v[190:191]
	v_bfe_u32 v21, v8, 16, 1
	v_bfe_u32 v7, v18, 16, 1
	v_bfe_u32 v20, v19, 16, 1
	v_bfe_u32 v22, v9, 16, 1
	v_add3_u32 v7, v18, v7, s26
	v_add3_u32 v8, v8, v21, s26
	v_add3_u32 v18, v19, v20, s26
	v_add3_u32 v9, v9, v22, s26
	v_lshrrev_b32_e32 v7, 16, v7
	v_lshrrev_b32_e32 v19, 16, v8
	v_and_or_b32 v8, v18, s27, v7
	v_and_or_b32 v9, v9, s27, v19
	global_store_dwordx2 v[76:77], v[8:9], off
	v_pk_mul_f32 v[8:9], v[16:17], v[6:7] op_sel_hi:[1,0]
	v_pk_mul_f32 v[14:15], v[14:15], v[6:7] op_sel_hi:[1,0]
	v_pk_mul_f32 v[8:9], v[164:165], v[8:9]
	v_pk_mul_f32 v[14:15], v[162:163], v[14:15]
	v_pk_add_f32 v[16:17], v[180:181], 1.0 op_sel_hi:[1,0]
	v_pk_add_f32 v[18:19], v[178:179], 1.0 op_sel_hi:[1,0]
	v_pk_fma_f32 v[8:9], v[16:17], v[8:9], v[196:197]
	v_pk_fma_f32 v[14:15], v[18:19], v[14:15], v[194:195]
	v_bfe_u32 v17, v8, 16, 1
	v_bfe_u32 v7, v14, 16, 1
	v_bfe_u32 v16, v15, 16, 1
	v_bfe_u32 v18, v9, 16, 1
	v_add3_u32 v7, v14, v7, s26
	v_add3_u32 v8, v8, v17, s26
	v_add3_u32 v14, v15, v16, s26
	v_add3_u32 v9, v9, v18, s26
	v_lshrrev_b32_e32 v7, 16, v7
	v_lshrrev_b32_e32 v15, 16, v8
	v_and_or_b32 v8, v14, s27, v7
	v_and_or_b32 v9, v9, s27, v15
	global_store_dwordx2 v[76:77], v[8:9], off offset:512
	v_pk_mul_f32 v[8:9], v[12:13], v[6:7] op_sel_hi:[1,0]
	v_pk_mul_f32 v[10:11], v[10:11], v[6:7] op_sel_hi:[1,0]
	v_pk_mul_f32 v[8:9], v[168:169], v[8:9]
	v_pk_mul_f32 v[10:11], v[166:167], v[10:11]
	v_pk_add_f32 v[12:13], v[184:185], 1.0 op_sel_hi:[1,0]
	v_pk_add_f32 v[14:15], v[182:183], 1.0 op_sel_hi:[1,0]
	v_pk_fma_f32 v[8:9], v[8:9], v[12:13], v[208:209]
	v_pk_fma_f32 v[10:11], v[10:11], v[14:15], v[206:207]
	v_bfe_u32 v13, v8, 16, 1
	v_bfe_u32 v7, v10, 16, 1
	v_bfe_u32 v12, v11, 16, 1
	v_bfe_u32 v14, v9, 16, 1
	v_add3_u32 v7, v10, v7, s26
	v_add3_u32 v8, v8, v13, s26
	v_add3_u32 v10, v11, v12, s26
	v_add3_u32 v9, v9, v14, s26
	v_lshrrev_b32_e32 v7, 16, v7
	v_lshrrev_b32_e32 v11, 16, v8
	v_and_or_b32 v8, v10, s27, v7
	v_and_or_b32 v9, v9, s27, v11
	global_store_dwordx2 v[76:77], v[8:9], off offset:1024
	s_nop 0
	v_pk_mul_f32 v[4:5], v[4:5], v[6:7] op_sel_hi:[1,0]
	v_pk_mul_f32 v[2:3], v[2:3], v[6:7] op_sel_hi:[1,0]
	v_pk_mul_f32 v[4:5], v[4:5], v[172:173]
	v_pk_mul_f32 v[2:3], v[2:3], v[170:171]
	v_pk_add_f32 v[6:7], v[188:189], 1.0 op_sel_hi:[1,0]
	v_pk_add_f32 v[8:9], v[186:187], 1.0 op_sel_hi:[1,0]
	v_pk_fma_f32 v[4:5], v[4:5], v[6:7], v[212:213]
	v_pk_fma_f32 v[2:3], v[2:3], v[8:9], v[210:211]
	v_cvt_pk_bf16_f32 v2, v2, v3
	v_cvt_pk_bf16_f32 v3, v4, v5
	global_store_dwordx2 v[76:77], v[2:3], off offset:1536
	s_cbranch_scc1 .LBB0_138
	v_readlane_b32 s16, v251, 9
	v_readlane_b32 s17, v251, 10
	v_readlane_b32 s18, v251, 11
	v_readlane_b32 s19, v251, 12
	v_readlane_b32 s20, v251, 13
	v_readlane_b32 s21, v251, 14
	v_readlane_b32 s22, v251, 15
	v_readlane_b32 s23, v251, 16
	v_readlane_b32 s24, v251, 17
	v_readlane_b32 s25, v251, 18
	v_readlane_b32 s26, v251, 19
	v_readlane_b32 s27, v251, 20
	v_readlane_b32 s28, v251, 21
	v_readlane_b32 s29, v251, 22
	v_readlane_b32 s30, v251, 23
	v_readlane_b32 s31, v251, 24
	v_readlane_b32 s16, v251, 25
	v_readlane_b32 s17, v251, 26
	v_readlane_b32 s18, v251, 27
	v_readlane_b32 s19, v251, 28
	v_readlane_b32 s20, v251, 29
	v_readlane_b32 s21, v251, 30
	v_readlane_b32 s22, v251, 31
	v_readlane_b32 s23, v251, 32
	v_readlane_b32 s24, v251, 33
	v_readlane_b32 s25, v251, 34
	v_readlane_b32 s26, v251, 35
	v_readlane_b32 s27, v251, 36
	v_readlane_b32 s28, v251, 37
	v_readlane_b32 s29, v251, 38
	v_readlane_b32 s30, v251, 39
	v_readlane_b32 s31, v251, 40

.LBB0_495:
	s_nop 0
	v_lshl_add_u64 v[8:9], s[34:35], 0, v[130:131]
	v_add_co_u32_e32 v8, vcc, s11, v8
	s_addk_i32 s10, 0x2000
	s_nop 0
	v_addc_co_u32_e32 v9, vcc, 0, v9, vcc
	global_load_dwordx4 v[84:87], v[8:9], off
	global_load_dwordx4 v[80:83], v[8:9], off offset:256
	v_lshl_add_u64 v[8:9], s[34:35], 0, v[128:129]
	v_add_co_u32_e32 v10, vcc, s12, v8
	v_lshl_add_u64 v[128:129], v[128:129], 0, s[6:7]
	s_nop 0
	v_addc_co_u32_e32 v11, vcc, 0, v9, vcc
	global_load_dword v151, v[10:11], off
	v_add_co_u32_e32 v10, vcc, s13, v8
	v_lshl_add_u64 v[130:131], v[130:131], 0, s[8:9]
	s_nop 0
	v_addc_co_u32_e32 v11, vcc, 0, v9, vcc
	v_add_co_u32_e32 v8, vcc, s16, v8
	global_load_dword v152, v[10:11], off
	s_nop 0
	v_addc_co_u32_e32 v9, vcc, 0, v9, vcc
	global_load_dword v153, v[8:9], off
	v_lshl_add_u64 v[8:9], s[34:35], 0, v[126:127]
	v_add_co_u32_e32 v10, vcc, s17, v8
	v_lshl_add_u64 v[126:127], v[126:127], 0, s[4:5]
	s_nop 0
	v_addc_co_u32_e32 v11, vcc, 0, v9, vcc
	global_load_dwordx4 v[72:75], v[10:11], off
	v_add_co_u32_e32 v10, vcc, s18, v8
	s_cmpk_lt_i32 s10, 0x2000
	s_nop 0
	v_addc_co_u32_e32 v11, vcc, 0, v9, vcc
	v_add_co_u32_e32 v8, vcc, s19, v8
	global_load_dwordx4 v[76:79], v[10:11], off
	s_nop 0
	v_addc_co_u32_e32 v9, vcc, 0, v9, vcc
	global_load_dwordx4 v[68:71], v[8:9], off
	v_lshl_add_u64 v[8:9], s[34:35], 0, v[116:117]
	v_add_co_u32_e32 v8, vcc, s11, v8
	v_lshl_add_u64 v[116:117], v[116:117], 0, s[8:9]
	s_nop 0
	v_addc_co_u32_e32 v9, vcc, 0, v9, vcc
	global_load_dwordx4 v[64:67], v[8:9], off
	global_load_dwordx4 v[60:63], v[8:9], off offset:256
	v_lshl_add_u64 v[8:9], s[34:35], 0, v[114:115]
	v_add_co_u32_e32 v10, vcc, s12, v8
	v_lshl_add_u64 v[114:115], v[114:115], 0, s[6:7]
	s_nop 0
	v_addc_co_u32_e32 v11, vcc, 0, v9, vcc
	global_load_dword v148, v[10:11], off
	v_add_co_u32_e32 v10, vcc, s13, v8
	s_waitcnt vmcnt(10)
	v_lshlrev_b32_e32 v155, 16, v85
	v_addc_co_u32_e32 v11, vcc, 0, v9, vcc
	v_add_co_u32_e32 v8, vcc, s16, v8
	global_load_dword v149, v[10:11], off
	s_nop 0
	v_addc_co_u32_e32 v9, vcc, 0, v9, vcc
	global_load_dword v150, v[8:9], off
	v_lshl_add_u64 v[8:9], s[34:35], 0, v[112:113]
	v_add_co_u32_e32 v10, vcc, s17, v8
	v_lshlrev_b32_e32 v154, 16, v84
	s_nop 0
	v_addc_co_u32_e32 v11, vcc, 0, v9, vcc
	global_load_dwordx4 v[52:55], v[10:11], off
	v_add_co_u32_e32 v10, vcc, s18, v8
	s_waitcnt vmcnt(12)
	v_lshlrev_b32_e32 v157, 16, v81
	v_addc_co_u32_e32 v11, vcc, 0, v9, vcc
	v_add_co_u32_e32 v8, vcc, s19, v8
	v_lshlrev_b32_e32 v156, 16, v80
	s_nop 0
	v_addc_co_u32_e32 v9, vcc, 0, v9, vcc
	v_and_b32_e32 v85, 0xffff0000, v85
	v_and_b32_e32 v84, 0xffff0000, v84
	v_and_b32_e32 v81, 0xffff0000, v81
	v_and_b32_e32 v80, 0xffff0000, v80
	global_load_dwordx4 v[56:59], v[10:11], off
	global_load_dwordx4 v[48:51], v[8:9], off
	v_lshl_add_u64 v[8:9], s[34:35], 0, v[106:107]
	v_pk_fma_f32 v[154:155], v[122:123], v[156:157], v[154:155] neg_lo:[1,0,0] neg_hi:[1,0,0]
	v_pk_fma_f32 v[80:81], v[122:123], v[80:81], v[84:85] neg_lo:[1,0,0] neg_hi:[1,0,0]
	v_add_co_u32_e32 v8, vcc, s11, v8
	v_pk_mul_f32 v[84:85], v[154:155], v[154:155]
	v_pk_mul_f32 v[156:157], v[80:81], v[80:81]
	v_lshlrev_b32_e32 v159, 16, v87
	v_lshlrev_b32_e32 v158, 16, v86
	v_lshlrev_b32_e32 v161, 16, v83
	v_lshlrev_b32_e32 v160, 16, v82
	v_and_b32_e32 v87, 0xffff0000, v87
	v_and_b32_e32 v86, 0xffff0000, v86
	v_and_b32_e32 v83, 0xffff0000, v83
	v_and_b32_e32 v82, 0xffff0000, v82
	v_addc_co_u32_e32 v9, vcc, 0, v9, vcc
	v_pk_fma_f32 v[158:159], v[122:123], v[160:161], v[158:159] neg_lo:[1,0,0] neg_hi:[1,0,0]
	v_pk_fma_f32 v[82:83], v[122:123], v[82:83], v[86:87] neg_lo:[1,0,0] neg_hi:[1,0,0]
	v_add_f32_e32 v84, v84, v156
	global_load_dwordx4 v[44:47], v[8:9], off
	global_load_dwordx4 v[40:43], v[8:9], off offset:256
	v_lshl_add_u64 v[8:9], s[34:35], 0, v[104:105]
	v_mov_b32_e32 v86, v82
	v_mov_b32_e32 v87, v158
	v_add_f32_e32 v84, v85, v84
	v_add_co_u32_e32 v10, vcc, s12, v8
	v_pk_mul_f32 v[86:87], v[86:87], v[86:87]
	v_add_f32_e32 v84, v157, v84
	v_addc_co_u32_e32 v11, vcc, 0, v9, vcc
	v_mov_b32_e32 v160, v83
	v_mov_b32_e32 v161, v159
	v_add_f32_e32 v84, v87, v84
	global_load_dword v145, v[10:11], off
	v_add_co_u32_e32 v10, vcc, s13, v8
	v_pk_mul_f32 v[160:161], v[160:161], v[160:161]
	v_add_f32_e32 v84, v86, v84
	v_addc_co_u32_e32 v11, vcc, 0, v9, vcc
	v_add_f32_e32 v84, v161, v84
	v_add_co_u32_e32 v8, vcc, s16, v8
	v_add_f32_e32 v84, v160, v84
	s_nop 0
	v_addc_co_u32_e32 v9, vcc, 0, v9, vcc
	ds_bpermute_b32 v85, v136, v84
	global_load_dword v146, v[10:11], off
	global_load_dword v147, v[8:9], off
	v_lshl_add_u64 v[8:9], s[34:35], 0, v[102:103]
	v_add_co_u32_e32 v10, vcc, s17, v8
	s_waitcnt lgkmcnt(0)
	v_add_f32_e32 v84, v84, v85
	v_addc_co_u32_e32 v11, vcc, 0, v9, vcc
	global_load_dwordx4 v[32:35], v[10:11], off
	v_add_co_u32_e32 v10, vcc, s18, v8
	ds_bpermute_b32 v85, v137, v84
	s_nop 0
	v_addc_co_u32_e32 v11, vcc, 0, v9, vcc
	v_add_co_u32_e32 v8, vcc, s19, v8
	global_load_dwordx4 v[36:39], v[10:11], off
	s_nop 0
	v_addc_co_u32_e32 v9, vcc, 0, v9, vcc
	global_load_dwordx4 v[28:31], v[8:9], off
	v_lshl_add_u64 v[8:9], s[34:35], 0, v[94:95]
	v_add_co_u32_e32 v8, vcc, s11, v8
	s_waitcnt lgkmcnt(0)
	v_add_f32_e32 v84, v84, v85
	v_addc_co_u32_e32 v9, vcc, 0, v9, vcc
	global_load_dwordx4 v[24:27], v[8:9], off
	global_load_dwordx4 v[20:23], v[8:9], off offset:256
	v_lshl_add_u64 v[8:9], s[34:35], 0, v[92:93]
	v_add_co_u32_e32 v10, vcc, s12, v8
	ds_bpermute_b32 v85, v138, v84
	s_nop 0
	v_addc_co_u32_e32 v11, vcc, 0, v9, vcc
	global_load_dword v142, v[10:11], off
	v_add_co_u32_e32 v10, vcc, s13, v8
	s_waitcnt lgkmcnt(0)
	v_add_f32_e32 v84, v84, v85
	v_addc_co_u32_e32 v11, vcc, 0, v9, vcc
	v_add_co_u32_e32 v8, vcc, s16, v8
	global_load_dword v143, v[10:11], off
	s_nop 0
	v_addc_co_u32_e32 v9, vcc, 0, v9, vcc
	global_load_dword v144, v[8:9], off
	v_lshl_add_u64 v[8:9], s[34:35], 0, v[90:91]
	ds_bpermute_b32 v85, v139, v84
	v_add_co_u32_e32 v10, vcc, s17, v8
	v_lshl_add_u64 v[90:91], v[90:91], 0, s[4:5]
	s_nop 0
	v_addc_co_u32_e32 v11, vcc, 0, v9, vcc
	global_load_dwordx4 v[12:15], v[10:11], off
	v_add_co_u32_e32 v10, vcc, s18, v8
	s_waitcnt lgkmcnt(0)
	v_add_f32_e32 v84, v84, v85
	v_addc_co_u32_e32 v11, vcc, 0, v9, vcc
	v_add_co_u32_e32 v8, vcc, s19, v8
	v_fmamk_f32 v84, v84, 0x3c000000, v140
	s_nop 0
	v_addc_co_u32_e32 v9, vcc, 0, v9, vcc
	v_cmp_gt_f32_e32 vcc, s21, v84
	v_mul_f32_e32 v85, 0x4f800000, v84
	global_load_dwordx4 v[16:19], v[10:11], off
	v_cndmask_b32_e32 v84, v84, v85, vcc
	v_sqrt_f32_e32 v85, v84
	global_load_dwordx4 v[8:11], v[8:9], off
	v_lshl_add_u64 v[92:93], v[92:93], 0, s[6:7]
	v_lshl_add_u64 v[94:95], v[94:95], 0, s[8:9]
	v_add_u32_e32 v86, -1, v85
	v_fma_f32 v87, -v86, v85, v84
	v_cmp_ge_f32_e64 s[0:1], 0, v87
	v_add_u32_e32 v87, 1, v85
	v_lshl_add_u64 v[102:103], v[102:103], 0, s[4:5]
	v_cndmask_b32_e64 v86, v85, v86, s[0:1]
	v_fma_f32 v85, -v87, v85, v84
	v_cmp_lt_f32_e64 s[0:1], 0, v85
	v_lshl_add_u64 v[104:105], v[104:105], 0, s[6:7]
	v_lshl_add_u64 v[106:107], v[106:107], 0, s[8:9]
	v_cndmask_b32_e64 v85, v86, v87, s[0:1]
	v_mul_f32_e32 v86, 0x37800000, v85
	v_cndmask_b32_e32 v85, v85, v86, vcc
	v_cmp_class_f32_e32 vcc, v84, v141
	v_lshl_add_u64 v[112:113], v[112:113], 0, s[4:5]
	s_nop 0
	v_cndmask_b32_e32 v84, v85, v84, vcc
	v_div_scale_f32 v85, s[0:1], v84, v84, s22
	v_rcp_f32_e32 v86, v85
	s_nop 0
	v_fma_f32 v87, -v85, v86, 1.0
	v_fmac_f32_e32 v86, v87, v86
	v_div_scale_f32 v87, vcc, s22, v84, s22
	v_mul_f32_e32 v156, v87, v86
	v_fma_f32 v157, -v85, v156, v87
	v_fmac_f32_e32 v156, v157, v86
	v_fma_f32 v85, -v85, v156, v87
	v_div_fmas_f32 v85, v85, v86, v156
	v_div_fixup_f32 v84, v85, v84, s22
	v_pk_mul_f32 v[82:83], v[82:83], v[84:85] op_sel_hi:[1,0]
	v_pk_mul_f32 v[86:87], v[154:155], v[84:85] op_sel_hi:[1,0]
	v_pk_mul_f32 v[82:83], v[4:5], v[82:83]
	v_pk_mul_f32 v[86:87], v[2:3], v[86:87]
	v_pk_mul_f32 v[80:81], v[80:81], v[84:85] op_sel_hi:[1,0]
	v_pk_mul_f32 v[154:155], v[158:159], v[84:85] op_sel_hi:[1,0]
	v_bfe_u32 v84, v83, 16, 1
	v_bfe_u32 v85, v82, 16, 1
	v_pk_mul_f32 v[80:81], v[124:125], v[80:81]
	v_add3_u32 v82, v82, v85, s23
	v_add3_u32 v83, v83, v84, s23
	v_cvt_pk_bf16_f32 v80, v86, v80
	v_cvt_pk_bf16_f32 v81, v87, v81
	v_pk_mul_f32 v[154:155], v[6:7], v[154:155]
	v_bfe_u32 v156, v154, 16, 1
	v_bfe_u32 v157, v155, 16, 1
	v_add3_u32 v155, v155, v157, s23
	v_add3_u32 v154, v154, v156, s23
	v_lshl_add_u64 v[84:85], v[100:101], 0, v[134:135]
	v_lshrrev_b32_e32 v86, 16, v154
	v_lshrrev_b32_e32 v87, 16, v155
	v_add_co_u32_e32 v84, vcc, s24, v84
	v_and_or_b32 v83, v83, s20, v87
	v_and_or_b32 v82, v82, s20, v86
	v_addc_co_u32_e32 v85, vcc, -1, v85, vcc
	global_store_dwordx4 v[84:85], v[80:83], off offset:-256 sc1
	v_lshl_add_u64 v[134:135], v[134:135], 0, s[8:9]
	s_waitcnt vmcnt(28)
	v_max3_f32 v80, v151, v152, v153
	v_sub_f32_e32 v81, v151, v80
	v_exp_f32_e32 v83, v81
	v_sub_f32_e32 v81, v152, v80
	v_exp_f32_e32 v82, v81
	v_sub_f32_e32 v80, v153, v80
	v_exp_f32_e32 v80, v80
	v_add_f32_e32 v81, v83, v82
	v_add_f32_e32 v81, v80, v81
	v_div_scale_f32 v84, s[0:1], v81, v81, 1.0
	v_rcp_f32_e32 v85, v84
	s_nop 0
	v_fma_f32 v86, -v84, v85, 1.0
	v_fmac_f32_e32 v85, v86, v85
	v_div_scale_f32 v86, vcc, 1.0, v81, 1.0
	v_mul_f32_e32 v87, v86, v85
	v_fma_f32 v151, -v84, v87, v86
	v_fmac_f32_e32 v87, v151, v85
	v_fma_f32 v84, -v84, v87, v86
	v_div_fmas_f32 v84, v84, v85, v87
	v_div_fixup_f32 v84, v84, v81, 1.0
	v_pk_mul_f32 v[82:83], v[82:83], v[84:85] op_sel_hi:[1,0]
	s_waitcnt vmcnt(26)
	v_lshlrev_b32_e32 v87, 16, v77
	v_lshlrev_b32_e32 v86, 16, v72
	v_mul_f32_e32 v80, v80, v84
	v_lshlrev_b32_e32 v85, 16, v73
	v_lshlrev_b32_e32 v84, 16, v76
	v_pk_mul_f32 v[86:87], v[82:83], v[86:87] op_sel:[1,0] op_sel_hi:[0,1]
	v_pk_fma_f32 v[84:85], v[82:83], v[84:85], v[86:87]
	s_waitcnt vmcnt(25)
	v_lshlrev_b32_e32 v87, 16, v69
	v_lshlrev_b32_e32 v86, 16, v68
	v_pk_fma_f32 v[84:85], v[80:81], v[86:87], v[84:85] op_sel_hi:[0,1,1]
	v_and_b32_e32 v87, 0xffff0000, v73
	v_and_b32_e32 v73, 0xffff0000, v77
	v_and_b32_e32 v72, 0xffff0000, v72
	v_and_b32_e32 v86, 0xffff0000, v76
	v_pk_mul_f32 v[72:73], v[82:83], v[72:73] op_sel:[1,0] op_sel_hi:[0,1]
	v_pk_fma_f32 v[72:73], v[82:83], v[86:87], v[72:73]
	v_and_b32_e32 v69, 0xffff0000, v69
	v_and_b32_e32 v68, 0xffff0000, v68
	v_lshlrev_b32_e32 v77, 16, v79
	v_lshlrev_b32_e32 v76, 16, v74
	v_pk_fma_f32 v[68:69], v[80:81], v[68:69], v[72:73] op_sel_hi:[0,1,1]
	v_lshlrev_b32_e32 v73, 16, v75
	v_lshlrev_b32_e32 v72, 16, v78
	v_pk_mul_f32 v[76:77], v[82:83], v[76:77] op_sel:[1,0] op_sel_hi:[0,1]
	v_pk_fma_f32 v[72:73], v[82:83], v[72:73], v[76:77]
	v_lshlrev_b32_e32 v77, 16, v71
	v_lshlrev_b32_e32 v76, 16, v70
	v_pk_fma_f32 v[72:73], v[80:81], v[76:77], v[72:73] op_sel_hi:[0,1,1]
	v_and_b32_e32 v77, 0xffff0000, v75
	v_and_b32_e32 v75, 0xffff0000, v79
	v_and_b32_e32 v74, 0xffff0000, v74
	v_and_b32_e32 v76, 0xffff0000, v78
	v_pk_mul_f32 v[74:75], v[82:83], v[74:75] op_sel:[1,0] op_sel_hi:[0,1]
	v_pk_fma_f32 v[74:75], v[82:83], v[76:77], v[74:75]
	v_and_b32_e32 v71, 0xffff0000, v71
	v_and_b32_e32 v70, 0xffff0000, v70
	v_cvt_pk_bf16_f32 v69, v85, v69
	v_cvt_pk_bf16_f32 v68, v84, v68
	v_pk_fma_f32 v[70:71], v[80:81], v[70:71], v[74:75] op_sel_hi:[0,1,1]
	v_cvt_pk_bf16_f32 v70, v72, v70
	v_cvt_pk_bf16_f32 v71, v73, v71
	v_lshl_add_u64 v[72:73], v[88:89], 0, v[132:133]
	v_add_co_u32_e32 v72, vcc, s25, v72
	v_addc_co_u32_e32 v73, vcc, -1, v73, vcc
	global_store_dwordx4 v[72:73], v[68:71], off offset:-3072 sc1
	s_waitcnt vmcnt(25)
	v_lshlrev_b32_e32 v73, 16, v67
	v_lshlrev_b32_e32 v72, 16, v66
	v_lshlrev_b32_e32 v69, 16, v65
	v_lshlrev_b32_e32 v68, 16, v64
	s_waitcnt vmcnt(24)
	v_lshlrev_b32_e32 v71, 16, v61
	v_lshlrev_b32_e32 v70, 16, v60
	v_and_b32_e32 v65, 0xffff0000, v65
	v_and_b32_e32 v64, 0xffff0000, v64
	v_and_b32_e32 v61, 0xffff0000, v61
	v_and_b32_e32 v60, 0xffff0000, v60
	v_pk_fma_f32 v[68:69], v[122:123], v[70:71], v[68:69] neg_lo:[1,0,0] neg_hi:[1,0,0]
	v_pk_fma_f32 v[60:61], v[122:123], v[60:61], v[64:65] neg_lo:[1,0,0] neg_hi:[1,0,0]
	v_pk_mul_f32 v[64:65], v[68:69], v[68:69]
	v_pk_mul_f32 v[70:71], v[60:61], v[60:61]
	v_lshlrev_b32_e32 v75, 16, v63
	v_lshlrev_b32_e32 v74, 16, v62
	v_and_b32_e32 v67, 0xffff0000, v67
	v_and_b32_e32 v66, 0xffff0000, v66
	v_and_b32_e32 v63, 0xffff0000, v63
	v_and_b32_e32 v62, 0xffff0000, v62
	v_pk_fma_f32 v[72:73], v[122:123], v[74:75], v[72:73] neg_lo:[1,0,0] neg_hi:[1,0,0]
	v_pk_fma_f32 v[62:63], v[122:123], v[62:63], v[66:67] neg_lo:[1,0,0] neg_hi:[1,0,0]
	v_add_f32_e32 v64, v64, v70
	v_mov_b32_e32 v66, v62
	v_mov_b32_e32 v67, v72
	v_add_f32_e32 v64, v65, v64
	v_pk_mul_f32 v[66:67], v[66:67], v[66:67]
	v_add_f32_e32 v64, v71, v64
	v_mov_b32_e32 v74, v63
	v_mov_b32_e32 v75, v73
	v_add_f32_e32 v64, v67, v64
	v_pk_mul_f32 v[74:75], v[74:75], v[74:75]
	v_add_f32_e32 v64, v66, v64
	v_add_f32_e32 v64, v75, v64
	v_add_f32_e32 v64, v74, v64
	ds_bpermute_b32 v65, v136, v64
	v_lshl_add_u64 v[132:133], v[132:133], 0, s[8:9]
	s_waitcnt lgkmcnt(0)
	v_add_f32_e32 v64, v64, v65
	ds_bpermute_b32 v65, v137, v64
	s_waitcnt lgkmcnt(0)
	v_add_f32_e32 v64, v64, v65
	ds_bpermute_b32 v65, v138, v64
	s_waitcnt lgkmcnt(0)
	v_add_f32_e32 v64, v64, v65
	ds_bpermute_b32 v65, v139, v64
	s_waitcnt lgkmcnt(0)
	v_add_f32_e32 v64, v64, v65
	v_fmamk_f32 v64, v64, 0x3c000000, v140
	v_cmp_gt_f32_e32 vcc, s21, v64
	v_mul_f32_e32 v65, 0x4f800000, v64
	s_nop 0
	v_cndmask_b32_e32 v64, v64, v65, vcc
	v_sqrt_f32_e32 v65, v64
	s_nop 0
	v_add_u32_e32 v66, -1, v65
	v_fma_f32 v67, -v66, v65, v64
	v_cmp_ge_f32_e64 s[0:1], 0, v67
	v_add_u32_e32 v67, 1, v65
	s_nop 0
	v_cndmask_b32_e64 v66, v65, v66, s[0:1]
	v_fma_f32 v65, -v67, v65, v64
	v_cmp_lt_f32_e64 s[0:1], 0, v65
	s_nop 1
	v_cndmask_b32_e64 v65, v66, v67, s[0:1]
	v_mul_f32_e32 v66, 0x37800000, v65
	v_cndmask_b32_e32 v65, v65, v66, vcc
	v_cmp_class_f32_e32 vcc, v64, v141
	s_nop 1
	v_cndmask_b32_e32 v64, v65, v64, vcc
	v_div_scale_f32 v65, s[0:1], v64, v64, s22
	v_rcp_f32_e32 v66, v65
	s_nop 0
	v_fma_f32 v67, -v65, v66, 1.0
	v_fmac_f32_e32 v66, v67, v66
	v_div_scale_f32 v67, vcc, s22, v64, s22
	v_mul_f32_e32 v70, v67, v66
	v_fma_f32 v71, -v65, v70, v67
	v_fmac_f32_e32 v70, v71, v66
	v_fma_f32 v65, -v65, v70, v67
	v_div_fmas_f32 v65, v65, v66, v70
	v_div_fixup_f32 v64, v65, v64, s22
	v_pk_mul_f32 v[62:63], v[62:63], v[64:65] op_sel_hi:[1,0]
	v_pk_mul_f32 v[66:67], v[68:69], v[64:65] op_sel_hi:[1,0]
	v_pk_mul_f32 v[62:63], v[4:5], v[62:63]
	v_pk_mul_f32 v[66:67], v[2:3], v[66:67]
	v_pk_mul_f32 v[60:61], v[60:61], v[64:65] op_sel_hi:[1,0]
	v_pk_mul_f32 v[68:69], v[72:73], v[64:65] op_sel_hi:[1,0]
	v_bfe_u32 v64, v63, 16, 1
	v_bfe_u32 v65, v62, 16, 1
	v_pk_mul_f32 v[60:61], v[124:125], v[60:61]
	v_add3_u32 v62, v62, v65, s23
	v_add3_u32 v63, v63, v64, s23
	v_cvt_pk_bf16_f32 v60, v66, v60
	v_cvt_pk_bf16_f32 v61, v67, v61
	v_pk_mul_f32 v[68:69], v[6:7], v[68:69]
	v_bfe_u32 v70, v68, 16, 1
	v_bfe_u32 v71, v69, 16, 1
	v_add3_u32 v69, v69, v71, s23
	v_add3_u32 v68, v68, v70, s23
	v_lshl_add_u64 v[64:65], v[100:101], 0, v[120:121]
	v_lshrrev_b32_e32 v66, 16, v68
	v_lshrrev_b32_e32 v67, 16, v69
	v_add_co_u32_e32 v64, vcc, s24, v64
	v_and_or_b32 v63, v63, s20, v67
	v_and_or_b32 v62, v62, s20, v66
	v_addc_co_u32_e32 v65, vcc, -1, v65, vcc
	global_store_dwordx4 v[64:65], v[60:63], off offset:-256 sc1
	v_lshl_add_u64 v[120:121], v[120:121], 0, s[8:9]
	s_waitcnt vmcnt(22)
	v_max3_f32 v60, v148, v149, v150
	v_sub_f32_e32 v61, v148, v60
	v_exp_f32_e32 v63, v61
	v_sub_f32_e32 v61, v149, v60
	v_exp_f32_e32 v62, v61
	v_sub_f32_e32 v60, v150, v60
	v_exp_f32_e32 v60, v60
	v_add_f32_e32 v61, v63, v62
	v_add_f32_e32 v61, v60, v61
	v_div_scale_f32 v64, s[0:1], v61, v61, 1.0
	v_rcp_f32_e32 v65, v64
	s_nop 0
	v_fma_f32 v66, -v64, v65, 1.0
	v_fmac_f32_e32 v65, v66, v65
	v_div_scale_f32 v66, vcc, 1.0, v61, 1.0
	v_mul_f32_e32 v67, v66, v65
	v_fma_f32 v68, -v64, v67, v66
	v_fmac_f32_e32 v67, v68, v65
	v_fma_f32 v64, -v64, v67, v66
	v_div_fmas_f32 v64, v64, v65, v67
	v_div_fixup_f32 v64, v64, v61, 1.0
	v_pk_mul_f32 v[62:63], v[62:63], v[64:65] op_sel_hi:[1,0]
	s_waitcnt vmcnt(20)
	v_lshlrev_b32_e32 v67, 16, v57
	v_lshlrev_b32_e32 v66, 16, v52
	v_mul_f32_e32 v60, v60, v64
	v_lshlrev_b32_e32 v65, 16, v53
	v_lshlrev_b32_e32 v64, 16, v56
	v_pk_mul_f32 v[66:67], v[62:63], v[66:67] op_sel:[1,0] op_sel_hi:[0,1]
	v_pk_fma_f32 v[64:65], v[62:63], v[64:65], v[66:67]
	s_waitcnt vmcnt(19)
	v_lshlrev_b32_e32 v67, 16, v49
	v_lshlrev_b32_e32 v66, 16, v48
	v_pk_fma_f32 v[64:65], v[60:61], v[66:67], v[64:65] op_sel_hi:[0,1,1]
	v_and_b32_e32 v67, 0xffff0000, v53
	v_and_b32_e32 v53, 0xffff0000, v57
	v_and_b32_e32 v52, 0xffff0000, v52
	v_and_b32_e32 v66, 0xffff0000, v56
	v_pk_mul_f32 v[52:53], v[62:63], v[52:53] op_sel:[1,0] op_sel_hi:[0,1]
	v_pk_fma_f32 v[52:53], v[62:63], v[66:67], v[52:53]
	v_and_b32_e32 v49, 0xffff0000, v49
	v_and_b32_e32 v48, 0xffff0000, v48
	v_lshlrev_b32_e32 v57, 16, v59
	v_lshlrev_b32_e32 v56, 16, v54
	v_pk_fma_f32 v[48:49], v[60:61], v[48:49], v[52:53] op_sel_hi:[0,1,1]
	v_lshlrev_b32_e32 v53, 16, v55
	v_lshlrev_b32_e32 v52, 16, v58
	v_pk_mul_f32 v[56:57], v[62:63], v[56:57] op_sel:[1,0] op_sel_hi:[0,1]
	v_pk_fma_f32 v[52:53], v[62:63], v[52:53], v[56:57]
	v_lshlrev_b32_e32 v57, 16, v51
	v_lshlrev_b32_e32 v56, 16, v50
	v_pk_fma_f32 v[52:53], v[60:61], v[56:57], v[52:53] op_sel_hi:[0,1,1]
	v_and_b32_e32 v57, 0xffff0000, v55
	v_and_b32_e32 v55, 0xffff0000, v59
	v_and_b32_e32 v54, 0xffff0000, v54
	v_and_b32_e32 v56, 0xffff0000, v58
	v_pk_mul_f32 v[54:55], v[62:63], v[54:55] op_sel:[1,0] op_sel_hi:[0,1]
	v_pk_fma_f32 v[54:55], v[62:63], v[56:57], v[54:55]
	v_and_b32_e32 v51, 0xffff0000, v51
	v_and_b32_e32 v50, 0xffff0000, v50
	v_cvt_pk_bf16_f32 v49, v65, v49
	v_cvt_pk_bf16_f32 v48, v64, v48
	v_pk_fma_f32 v[50:51], v[60:61], v[50:51], v[54:55] op_sel_hi:[0,1,1]
	v_cvt_pk_bf16_f32 v50, v52, v50
	v_cvt_pk_bf16_f32 v51, v53, v51
	v_lshl_add_u64 v[52:53], v[88:89], 0, v[118:119]
	v_add_co_u32_e32 v52, vcc, s25, v52
	v_addc_co_u32_e32 v53, vcc, -1, v53, vcc
	global_store_dwordx4 v[52:53], v[48:51], off offset:-3072 sc1
	s_waitcnt vmcnt(19)
	v_lshlrev_b32_e32 v53, 16, v47
	v_lshlrev_b32_e32 v52, 16, v46
	v_lshlrev_b32_e32 v49, 16, v45
	v_lshlrev_b32_e32 v48, 16, v44
	s_waitcnt vmcnt(18)
	v_lshlrev_b32_e32 v51, 16, v41
	v_lshlrev_b32_e32 v50, 16, v40
	v_and_b32_e32 v45, 0xffff0000, v45
	v_and_b32_e32 v44, 0xffff0000, v44
	v_and_b32_e32 v41, 0xffff0000, v41
	v_and_b32_e32 v40, 0xffff0000, v40
	v_pk_fma_f32 v[48:49], v[122:123], v[50:51], v[48:49] neg_lo:[1,0,0] neg_hi:[1,0,0]
	v_pk_fma_f32 v[40:41], v[122:123], v[40:41], v[44:45] neg_lo:[1,0,0] neg_hi:[1,0,0]
	v_pk_mul_f32 v[44:45], v[48:49], v[48:49]
	v_pk_mul_f32 v[50:51], v[40:41], v[40:41]
	v_lshlrev_b32_e32 v55, 16, v43
	v_lshlrev_b32_e32 v54, 16, v42
	v_and_b32_e32 v47, 0xffff0000, v47
	v_and_b32_e32 v46, 0xffff0000, v46
	v_and_b32_e32 v43, 0xffff0000, v43
	v_and_b32_e32 v42, 0xffff0000, v42
	v_pk_fma_f32 v[52:53], v[122:123], v[54:55], v[52:53] neg_lo:[1,0,0] neg_hi:[1,0,0]
	v_pk_fma_f32 v[42:43], v[122:123], v[42:43], v[46:47] neg_lo:[1,0,0] neg_hi:[1,0,0]
	v_add_f32_e32 v44, v44, v50
	v_mov_b32_e32 v46, v42
	v_mov_b32_e32 v47, v52
	v_add_f32_e32 v44, v45, v44
	v_pk_mul_f32 v[46:47], v[46:47], v[46:47]
	v_add_f32_e32 v44, v51, v44
	v_mov_b32_e32 v54, v43
	v_mov_b32_e32 v55, v53
	v_add_f32_e32 v44, v47, v44
	v_pk_mul_f32 v[54:55], v[54:55], v[54:55]
	v_add_f32_e32 v44, v46, v44
	v_add_f32_e32 v44, v55, v44
	v_add_f32_e32 v44, v54, v44
	ds_bpermute_b32 v45, v136, v44
	v_lshl_add_u64 v[118:119], v[118:119], 0, s[8:9]
	s_waitcnt lgkmcnt(0)
	v_add_f32_e32 v44, v44, v45
	ds_bpermute_b32 v45, v137, v44
	s_waitcnt lgkmcnt(0)
	v_add_f32_e32 v44, v44, v45
	ds_bpermute_b32 v45, v138, v44
	s_waitcnt lgkmcnt(0)
	v_add_f32_e32 v44, v44, v45
	ds_bpermute_b32 v45, v139, v44
	s_waitcnt lgkmcnt(0)
	v_add_f32_e32 v44, v44, v45
	v_fmamk_f32 v44, v44, 0x3c000000, v140
	v_cmp_gt_f32_e32 vcc, s21, v44
	v_mul_f32_e32 v45, 0x4f800000, v44
	s_nop 0
	v_cndmask_b32_e32 v44, v44, v45, vcc
	v_sqrt_f32_e32 v45, v44
	s_nop 0
	v_add_u32_e32 v46, -1, v45
	v_fma_f32 v47, -v46, v45, v44
	v_cmp_ge_f32_e64 s[0:1], 0, v47
	v_add_u32_e32 v47, 1, v45
	s_nop 0
	v_cndmask_b32_e64 v46, v45, v46, s[0:1]
	v_fma_f32 v45, -v47, v45, v44
	v_cmp_lt_f32_e64 s[0:1], 0, v45
	s_nop 1
	v_cndmask_b32_e64 v45, v46, v47, s[0:1]
	v_mul_f32_e32 v46, 0x37800000, v45
	v_cndmask_b32_e32 v45, v45, v46, vcc
	v_cmp_class_f32_e32 vcc, v44, v141
	s_nop 1
	v_cndmask_b32_e32 v44, v45, v44, vcc
	v_div_scale_f32 v45, s[0:1], v44, v44, s22
	v_rcp_f32_e32 v46, v45
	s_nop 0
	v_fma_f32 v47, -v45, v46, 1.0
	v_fmac_f32_e32 v46, v47, v46
	v_div_scale_f32 v47, vcc, s22, v44, s22
	v_mul_f32_e32 v50, v47, v46
	v_fma_f32 v51, -v45, v50, v47
	v_fmac_f32_e32 v50, v51, v46
	v_fma_f32 v45, -v45, v50, v47
	v_div_fmas_f32 v45, v45, v46, v50
	v_div_fixup_f32 v44, v45, v44, s22
	v_pk_mul_f32 v[42:43], v[42:43], v[44:45] op_sel_hi:[1,0]
	v_pk_mul_f32 v[46:47], v[48:49], v[44:45] op_sel_hi:[1,0]
	v_pk_mul_f32 v[42:43], v[4:5], v[42:43]
	v_pk_mul_f32 v[46:47], v[2:3], v[46:47]
	v_pk_mul_f32 v[40:41], v[40:41], v[44:45] op_sel_hi:[1,0]
	v_pk_mul_f32 v[48:49], v[52:53], v[44:45] op_sel_hi:[1,0]
	v_bfe_u32 v44, v43, 16, 1
	v_bfe_u32 v45, v42, 16, 1
	v_pk_mul_f32 v[40:41], v[124:125], v[40:41]
	v_add3_u32 v42, v42, v45, s23
	v_add3_u32 v43, v43, v44, s23
	v_cvt_pk_bf16_f32 v40, v46, v40
	v_cvt_pk_bf16_f32 v41, v47, v41
	v_pk_mul_f32 v[48:49], v[6:7], v[48:49]
	v_bfe_u32 v50, v48, 16, 1
	v_bfe_u32 v51, v49, 16, 1
	v_add3_u32 v49, v49, v51, s23
	v_add3_u32 v48, v48, v50, s23
	v_lshl_add_u64 v[44:45], v[100:101], 0, v[110:111]
	v_lshrrev_b32_e32 v46, 16, v48
	v_lshrrev_b32_e32 v47, 16, v49
	v_add_co_u32_e32 v44, vcc, s24, v44
	v_and_or_b32 v43, v43, s20, v47
	v_and_or_b32 v42, v42, s20, v46
	v_addc_co_u32_e32 v45, vcc, -1, v45, vcc
	global_store_dwordx4 v[44:45], v[40:43], off offset:-256 sc1
	v_lshl_add_u64 v[110:111], v[110:111], 0, s[8:9]
	s_waitcnt vmcnt(16)
	v_max3_f32 v40, v145, v146, v147
	v_sub_f32_e32 v41, v145, v40
	v_exp_f32_e32 v43, v41
	v_sub_f32_e32 v41, v146, v40
	v_exp_f32_e32 v42, v41
	v_sub_f32_e32 v40, v147, v40
	v_exp_f32_e32 v40, v40
	v_add_f32_e32 v41, v43, v42
	v_add_f32_e32 v41, v40, v41
	v_div_scale_f32 v44, s[0:1], v41, v41, 1.0
	v_rcp_f32_e32 v45, v44
	s_nop 0
	v_fma_f32 v46, -v44, v45, 1.0
	v_fmac_f32_e32 v45, v46, v45
	v_div_scale_f32 v46, vcc, 1.0, v41, 1.0
	v_mul_f32_e32 v47, v46, v45
	v_fma_f32 v48, -v44, v47, v46
	v_fmac_f32_e32 v47, v48, v45
	v_fma_f32 v44, -v44, v47, v46
	v_div_fmas_f32 v44, v44, v45, v47
	v_div_fixup_f32 v44, v44, v41, 1.0
	v_pk_mul_f32 v[42:43], v[42:43], v[44:45] op_sel_hi:[1,0]
	s_waitcnt vmcnt(14)
	v_lshlrev_b32_e32 v47, 16, v37
	v_lshlrev_b32_e32 v46, 16, v32
	v_mul_f32_e32 v40, v40, v44
	v_lshlrev_b32_e32 v45, 16, v33
	v_lshlrev_b32_e32 v44, 16, v36
	v_pk_mul_f32 v[46:47], v[42:43], v[46:47] op_sel:[1,0] op_sel_hi:[0,1]
	v_pk_fma_f32 v[44:45], v[42:43], v[44:45], v[46:47]
	s_waitcnt vmcnt(13)
	v_lshlrev_b32_e32 v47, 16, v29
	v_lshlrev_b32_e32 v46, 16, v28
	v_pk_fma_f32 v[44:45], v[40:41], v[46:47], v[44:45] op_sel_hi:[0,1,1]
	v_and_b32_e32 v47, 0xffff0000, v33
	v_and_b32_e32 v33, 0xffff0000, v37
	v_and_b32_e32 v32, 0xffff0000, v32
	v_and_b32_e32 v46, 0xffff0000, v36
	v_pk_mul_f32 v[32:33], v[42:43], v[32:33] op_sel:[1,0] op_sel_hi:[0,1]
	v_pk_fma_f32 v[32:33], v[42:43], v[46:47], v[32:33]
	v_and_b32_e32 v29, 0xffff0000, v29
	v_and_b32_e32 v28, 0xffff0000, v28
	v_lshlrev_b32_e32 v37, 16, v39
	v_lshlrev_b32_e32 v36, 16, v34
	v_pk_fma_f32 v[28:29], v[40:41], v[28:29], v[32:33] op_sel_hi:[0,1,1]
	v_lshlrev_b32_e32 v33, 16, v35
	v_lshlrev_b32_e32 v32, 16, v38
	v_pk_mul_f32 v[36:37], v[42:43], v[36:37] op_sel:[1,0] op_sel_hi:[0,1]
	v_pk_fma_f32 v[32:33], v[42:43], v[32:33], v[36:37]
	v_lshlrev_b32_e32 v37, 16, v31
	v_lshlrev_b32_e32 v36, 16, v30
	v_pk_fma_f32 v[32:33], v[40:41], v[36:37], v[32:33] op_sel_hi:[0,1,1]
	v_and_b32_e32 v37, 0xffff0000, v35
	v_and_b32_e32 v35, 0xffff0000, v39
	v_and_b32_e32 v34, 0xffff0000, v34
	v_and_b32_e32 v36, 0xffff0000, v38
	v_pk_mul_f32 v[34:35], v[42:43], v[34:35] op_sel:[1,0] op_sel_hi:[0,1]
	v_pk_fma_f32 v[34:35], v[42:43], v[36:37], v[34:35]
	v_and_b32_e32 v31, 0xffff0000, v31
	v_and_b32_e32 v30, 0xffff0000, v30
	v_cvt_pk_bf16_f32 v29, v45, v29
	v_cvt_pk_bf16_f32 v28, v44, v28
	v_pk_fma_f32 v[30:31], v[40:41], v[30:31], v[34:35] op_sel_hi:[0,1,1]
	v_cvt_pk_bf16_f32 v30, v32, v30
	v_cvt_pk_bf16_f32 v31, v33, v31
	v_lshl_add_u64 v[32:33], v[88:89], 0, v[108:109]
	v_add_co_u32_e32 v32, vcc, s25, v32
	v_addc_co_u32_e32 v33, vcc, -1, v33, vcc
	global_store_dwordx4 v[32:33], v[28:31], off offset:-3072 sc1
	s_waitcnt vmcnt(13)
	v_lshlrev_b32_e32 v33, 16, v27
	v_lshlrev_b32_e32 v32, 16, v26
	v_lshlrev_b32_e32 v29, 16, v25
	v_lshlrev_b32_e32 v28, 16, v24
	s_waitcnt vmcnt(12)
	v_lshlrev_b32_e32 v31, 16, v21
	v_lshlrev_b32_e32 v30, 16, v20
	v_and_b32_e32 v25, 0xffff0000, v25
	v_and_b32_e32 v24, 0xffff0000, v24
	v_and_b32_e32 v21, 0xffff0000, v21
	v_and_b32_e32 v20, 0xffff0000, v20
	v_pk_fma_f32 v[28:29], v[122:123], v[30:31], v[28:29] neg_lo:[1,0,0] neg_hi:[1,0,0]
	v_pk_fma_f32 v[20:21], v[122:123], v[20:21], v[24:25] neg_lo:[1,0,0] neg_hi:[1,0,0]
	v_pk_mul_f32 v[24:25], v[28:29], v[28:29]
	v_pk_mul_f32 v[30:31], v[20:21], v[20:21]
	v_lshlrev_b32_e32 v35, 16, v23
	v_lshlrev_b32_e32 v34, 16, v22
	v_and_b32_e32 v27, 0xffff0000, v27
	v_and_b32_e32 v26, 0xffff0000, v26
	v_and_b32_e32 v23, 0xffff0000, v23
	v_and_b32_e32 v22, 0xffff0000, v22
	v_pk_fma_f32 v[32:33], v[122:123], v[34:35], v[32:33] neg_lo:[1,0,0] neg_hi:[1,0,0]
	v_pk_fma_f32 v[22:23], v[122:123], v[22:23], v[26:27] neg_lo:[1,0,0] neg_hi:[1,0,0]
	v_add_f32_e32 v24, v24, v30
	v_mov_b32_e32 v26, v22
	v_mov_b32_e32 v27, v32
	v_add_f32_e32 v24, v25, v24
	v_pk_mul_f32 v[26:27], v[26:27], v[26:27]
	v_add_f32_e32 v24, v31, v24
	v_mov_b32_e32 v34, v23
	v_mov_b32_e32 v35, v33
	v_add_f32_e32 v24, v27, v24
	v_pk_mul_f32 v[34:35], v[34:35], v[34:35]
	v_add_f32_e32 v24, v26, v24
	v_add_f32_e32 v24, v35, v24
	v_add_f32_e32 v24, v34, v24
	ds_bpermute_b32 v25, v136, v24
	v_lshl_add_u64 v[108:109], v[108:109], 0, s[8:9]
	s_waitcnt lgkmcnt(0)
	v_add_f32_e32 v24, v24, v25
	ds_bpermute_b32 v25, v137, v24
	s_waitcnt lgkmcnt(0)
	v_add_f32_e32 v24, v24, v25
	ds_bpermute_b32 v25, v138, v24
	s_waitcnt lgkmcnt(0)
	v_add_f32_e32 v24, v24, v25
	ds_bpermute_b32 v25, v139, v24
	s_waitcnt lgkmcnt(0)
	v_add_f32_e32 v24, v24, v25
	v_fmamk_f32 v24, v24, 0x3c000000, v140
	v_cmp_gt_f32_e32 vcc, s21, v24
	v_mul_f32_e32 v25, 0x4f800000, v24
	s_nop 0
	v_cndmask_b32_e32 v24, v24, v25, vcc
	v_sqrt_f32_e32 v25, v24
	s_nop 0
	v_add_u32_e32 v26, -1, v25
	v_fma_f32 v27, -v26, v25, v24
	v_cmp_ge_f32_e64 s[0:1], 0, v27
	v_add_u32_e32 v27, 1, v25
	s_nop 0
	v_cndmask_b32_e64 v26, v25, v26, s[0:1]
	v_fma_f32 v25, -v27, v25, v24
	v_cmp_lt_f32_e64 s[0:1], 0, v25
	s_nop 1
	v_cndmask_b32_e64 v25, v26, v27, s[0:1]
	v_mul_f32_e32 v26, 0x37800000, v25
	v_cndmask_b32_e32 v25, v25, v26, vcc
	v_cmp_class_f32_e32 vcc, v24, v141
	s_nop 1
	v_cndmask_b32_e32 v24, v25, v24, vcc
	v_div_scale_f32 v25, s[0:1], v24, v24, s22
	v_rcp_f32_e32 v26, v25
	s_nop 0
	v_fma_f32 v27, -v25, v26, 1.0
	v_fmac_f32_e32 v26, v27, v26
	v_div_scale_f32 v27, vcc, s22, v24, s22
	v_mul_f32_e32 v30, v27, v26
	v_fma_f32 v31, -v25, v30, v27
	v_fmac_f32_e32 v30, v31, v26
	v_fma_f32 v25, -v25, v30, v27
	v_div_fmas_f32 v25, v25, v26, v30
	v_div_fixup_f32 v24, v25, v24, s22
	v_pk_mul_f32 v[22:23], v[22:23], v[24:25] op_sel_hi:[1,0]
	v_pk_mul_f32 v[26:27], v[28:29], v[24:25] op_sel_hi:[1,0]
	v_pk_mul_f32 v[22:23], v[4:5], v[22:23]
	v_pk_mul_f32 v[26:27], v[2:3], v[26:27]
	v_pk_mul_f32 v[20:21], v[20:21], v[24:25] op_sel_hi:[1,0]
	v_pk_mul_f32 v[28:29], v[32:33], v[24:25] op_sel_hi:[1,0]
	v_bfe_u32 v24, v23, 16, 1
	v_bfe_u32 v25, v22, 16, 1
	v_pk_mul_f32 v[20:21], v[124:125], v[20:21]
	v_add3_u32 v22, v22, v25, s23
	v_add3_u32 v23, v23, v24, s23
	v_cvt_pk_bf16_f32 v20, v26, v20
	v_cvt_pk_bf16_f32 v21, v27, v21
	v_pk_mul_f32 v[28:29], v[6:7], v[28:29]
	v_bfe_u32 v30, v28, 16, 1
	v_bfe_u32 v31, v29, 16, 1
	v_add3_u32 v29, v29, v31, s23
	v_add3_u32 v28, v28, v30, s23
	v_lshl_add_u64 v[24:25], v[100:101], 0, v[98:99]
	v_lshrrev_b32_e32 v26, 16, v28
	v_lshrrev_b32_e32 v27, 16, v29
	v_add_co_u32_e32 v24, vcc, s24, v24
	v_and_or_b32 v23, v23, s20, v27
	v_and_or_b32 v22, v22, s20, v26
	v_addc_co_u32_e32 v25, vcc, -1, v25, vcc
	global_store_dwordx4 v[24:25], v[20:23], off offset:-256 sc1
	v_lshl_add_u64 v[98:99], v[98:99], 0, s[8:9]
	s_waitcnt vmcnt(10)
	v_max3_f32 v20, v142, v143, v144
	v_sub_f32_e32 v21, v142, v20
	v_exp_f32_e32 v23, v21
	v_sub_f32_e32 v21, v143, v20
	v_exp_f32_e32 v22, v21
	v_sub_f32_e32 v20, v144, v20
	v_exp_f32_e32 v20, v20
	v_add_f32_e32 v21, v23, v22
	v_add_f32_e32 v21, v20, v21
	v_div_scale_f32 v24, s[0:1], v21, v21, 1.0
	v_rcp_f32_e32 v25, v24
	s_nop 0
	v_fma_f32 v26, -v24, v25, 1.0
	v_fmac_f32_e32 v25, v26, v25
	v_div_scale_f32 v26, vcc, 1.0, v21, 1.0
	v_mul_f32_e32 v27, v26, v25
	v_fma_f32 v28, -v24, v27, v26
	v_fmac_f32_e32 v27, v28, v25
	v_fma_f32 v24, -v24, v27, v26
	v_div_fmas_f32 v24, v24, v25, v27
	v_div_fixup_f32 v24, v24, v21, 1.0
	v_pk_mul_f32 v[22:23], v[22:23], v[24:25] op_sel_hi:[1,0]
	s_waitcnt vmcnt(8)
	v_lshlrev_b32_e32 v27, 16, v17
	v_lshlrev_b32_e32 v26, 16, v12
	v_mul_f32_e32 v20, v20, v24
	v_lshlrev_b32_e32 v25, 16, v13
	v_lshlrev_b32_e32 v24, 16, v16
	v_pk_mul_f32 v[26:27], v[22:23], v[26:27] op_sel:[1,0] op_sel_hi:[0,1]
	v_pk_fma_f32 v[24:25], v[22:23], v[24:25], v[26:27]
	s_waitcnt vmcnt(7)
	v_lshlrev_b32_e32 v27, 16, v9
	v_lshlrev_b32_e32 v26, 16, v8
	v_pk_fma_f32 v[24:25], v[20:21], v[26:27], v[24:25] op_sel_hi:[0,1,1]
	v_and_b32_e32 v27, 0xffff0000, v13
	v_and_b32_e32 v13, 0xffff0000, v17
	v_and_b32_e32 v12, 0xffff0000, v12
	v_and_b32_e32 v26, 0xffff0000, v16
	v_pk_mul_f32 v[12:13], v[22:23], v[12:13] op_sel:[1,0] op_sel_hi:[0,1]
	v_pk_fma_f32 v[12:13], v[22:23], v[26:27], v[12:13]
	v_and_b32_e32 v9, 0xffff0000, v9
	v_and_b32_e32 v8, 0xffff0000, v8
	v_lshlrev_b32_e32 v17, 16, v19
	v_lshlrev_b32_e32 v16, 16, v14
	v_pk_fma_f32 v[8:9], v[20:21], v[8:9], v[12:13] op_sel_hi:[0,1,1]
	v_lshlrev_b32_e32 v13, 16, v15
	v_lshlrev_b32_e32 v12, 16, v18
	v_pk_mul_f32 v[16:17], v[22:23], v[16:17] op_sel:[1,0] op_sel_hi:[0,1]
	v_pk_fma_f32 v[12:13], v[22:23], v[12:13], v[16:17]
	v_lshlrev_b32_e32 v17, 16, v11
	v_lshlrev_b32_e32 v16, 16, v10
	v_pk_fma_f32 v[12:13], v[20:21], v[16:17], v[12:13] op_sel_hi:[0,1,1]
	v_and_b32_e32 v17, 0xffff0000, v15
	v_and_b32_e32 v15, 0xffff0000, v19
	v_and_b32_e32 v14, 0xffff0000, v14
	v_and_b32_e32 v16, 0xffff0000, v18
	v_pk_mul_f32 v[14:15], v[22:23], v[14:15] op_sel:[1,0] op_sel_hi:[0,1]
	v_pk_fma_f32 v[14:15], v[22:23], v[16:17], v[14:15]
	v_and_b32_e32 v11, 0xffff0000, v11
	v_and_b32_e32 v10, 0xffff0000, v10
	v_cvt_pk_bf16_f32 v9, v25, v9
	v_cvt_pk_bf16_f32 v8, v24, v8
	v_pk_fma_f32 v[10:11], v[20:21], v[10:11], v[14:15] op_sel_hi:[0,1,1]
	v_cvt_pk_bf16_f32 v10, v12, v10
	v_cvt_pk_bf16_f32 v11, v13, v11
	v_lshl_add_u64 v[12:13], v[88:89], 0, v[96:97]
	v_add_co_u32_e32 v12, vcc, s25, v12
	v_addc_co_u32_e32 v13, vcc, -1, v13, vcc
	v_lshl_add_u64 v[96:97], v[96:97], 0, s[8:9]
	global_store_dwordx4 v[12:13], v[8:11], off offset:-3072 sc1
	s_cbranch_scc1 .LBB0_495
